# gate/up/in weight conversion routine: row loads widened from dword to dwordx4 (8 rows x 128 bytes per instruction), LDS write pattern adapted
# baseline (speedup 1.0000x reference)
.Lcva_done:
.LBB0_562:
	s_cmp_eq_u32 s80, 2
	v_readlane_b32 s7, v253, 43
	s_cselect_b64 s[0:1], -1, 0
	s_cmp_gt_i32 s7, 63
	s_cselect_b64 s[4:5], -1, 0
	s_and_b64 s[0:1], s[0:1], s[4:5]
	s_andn2_b64 vcc, exec, s[0:1]
	s_cbranch_vccnz .LBB0_584
	s_lshl_b32 s0, s7, 3
	v_readlane_b32 s4, v253, 45
	s_add_i32 s0, s0, s4
	s_add_i32 s6, s0, 0xfffffe00
	s_cmpk_gt_i32 s6, 0xf7f
	v_readlane_b32 s5, v253, 46
	s_cbranch_scc1 .LBB0_584
	s_mov_b32 s4, s6
	s_movk_i32 s24, 0x600
	s_movk_i32 s25, 0xf80
	v_readlane_b32 s0, v253, 45
	s_mulk_i32 s0, 0x4200
	s_add_i32 s0, s97, s0
	v_readlane_b32 s22, v253, 41
	v_readlane_b32 s23, v253, 42
	v_readlane_b32 s6, v252, 1
	v_readlane_b32 s7, v252, 2
	s_load_dwordx4 s[8:11], s[6:7], 0x48
	s_load_dwordx2 s[14:15], s[6:7], 0x60
	v_lshrrev_b32_e32 v12, 3, v238
	v_and_b32_e32 v7, 7, v238
	v_lshlrev_b32_e32 v11, 3, v7
	v_lshlrev_b32_e32 v10, 1, v11
	v_lshl_add_u32 v4, v12, 11, v10
	v_mul_u32_u24_e32 v2, 0x84, v12
	v_lshrrev_b32_e32 v8, 1, v7
	v_and_b32_e32 v9, 1, v7
	v_lshlrev_b32_e32 v0, 4, v8
	v_lshl_add_u32 v0, v9, 6, v0
	v_add3_u32 v13, s0, v0, v2
	v_add_u32_e32 v14, 0x420, v13
	v_add_u32_e32 v15, 0x840, v13
	v_add_u32_e32 v16, 0xc60, v13
	v_add_u32_e32 v17, 0x1080, v13
	v_add_u32_e32 v18, 0x14a0, v13
	v_add_u32_e32 v19, 0x18c0, v13
	v_add_u32_e32 v20, 0x1ce0, v13
	v_mul_u32_u24_e32 v3, 0x2100, v9
	v_lshl_add_u32 v0, v8, 4, v3
	v_add3_u32 v144, s0, v0, v2
	v_add_u32_e32 v145, 0x420, v144
	v_add_u32_e32 v146, 0x840, v144
	v_add_u32_e32 v147, 0xc60, v144
	v_add_u32_e32 v148, 0x1080, v144
	v_add_u32_e32 v149, 0x14a0, v144
	v_add_u32_e32 v150, 0x18c0, v144
	v_add_u32_e32 v151, 0x1ce0, v144
	v_add_u32_e32 v152, 64, v144
	v_add_u32_e32 v153, 64, v145
	v_add_u32_e32 v154, 64, v146
	v_add_u32_e32 v155, 64, v147
	v_add_u32_e32 v156, 64, v148
	v_add_u32_e32 v157, 64, v149
	v_add_u32_e32 v158, 64, v150
	v_add_u32_e32 v159, 64, v151
	v_mul_u32_u24_e32 v10, 0x84, v11
	v_lshlrev_b32_e32 v2, 2, v12
	v_add3_u32 v21, s0, v10, v2
	v_mov_b32_e32 v11, v1
	v_lshlrev_b32_e32 v8, 4, v7
	s_waitcnt lgkmcnt(0)
	v_mul_u32_u24_e32 v10, 0x2c00, v12
	v_add_u32_e32 v10, v10, v8
	v_lshl_add_u64 v[136:137], s[8:9], 0, v[10:11]
	v_lshl_add_u64 v[138:139], s[10:11], 0, v[10:11]
	v_mul_u32_u24_e32 v10, 0x2400, v12
	v_add_u32_e32 v10, v10, v8
	v_lshl_add_u64 v[140:141], s[14:15], 0, v[10:11]
	s_cmpk_lt_u32 s4, 0xb00
	s_cbranch_scc0 .Lcvc_in1
	s_cmpk_gt_u32 s4, 0x57f
	s_cselect_b32 s5, 1, 0
	s_mul_i32 s6, s5, 0x580
	s_sub_i32 s6, s4, s6
	s_mul_i32 s7, s6, 0x2e9
	s_lshr_b32 s7, s7, 16
	s_mul_i32 s8, s7, 0x58
	s_sub_i32 s6, s6, s8
	s_lshr_b32 s8, s6, 2
	s_and_b32 s9, s6, 3
	s_lshl_b32 s10, s8, 9
	s_lshl_b32 s11, s9, 7
	s_add_i32 s10, s10, s11
	s_mul_i32 s11, s5, 0xb00000
	s_add_u32 s10, s10, s11
	s_add_u32 s10, s10, 0x1600000
	s_mul_i32 s11, s7, 0xb0000
	s_add_u32 s10, s10, s11
	s_mov_b32 s11, 0
	v_lshl_add_u64 v[22:23], v[136:137], 0, s[10:11]
	v_lshl_add_u64 v[142:143], v[138:139], 0, s[10:11]
	s_mov_b64 s[26:27], 0x16000
	s_lshl_b32 s8, s8, 3
	s_add_i32 s8, s8, s9
	s_mul_i32 s9, s5, 0xf80000
	s_lshl_b32 s8, s8, 16
	s_add_u32 s8, s8, s9
	s_lshl_b32 s9, s7, 7
	s_add_u32 s8, s8, s9
	s_add_u32 s8, s8, 0x3780000
	s_add_u32 s12, s22, s8
	s_addc_u32 s13, s23, 0
	s_mov_b32 s1, 1
	global_load_dwordx4 v[24:27], v[22:23], off nt
	v_lshl_add_u64 v[22:23], v[22:23], 0, s[26:27]
	global_load_dwordx4 v[28:31], v[22:23], off nt
	v_lshl_add_u64 v[22:23], v[22:23], 0, s[26:27]
	global_load_dwordx4 v[32:35], v[22:23], off nt
	v_lshl_add_u64 v[22:23], v[22:23], 0, s[26:27]
	global_load_dwordx4 v[36:39], v[22:23], off nt
	v_lshl_add_u64 v[22:23], v[22:23], 0, s[26:27]
	global_load_dwordx4 v[40:43], v[22:23], off nt
	v_lshl_add_u64 v[22:23], v[22:23], 0, s[26:27]
	global_load_dwordx4 v[44:47], v[22:23], off nt
	v_lshl_add_u64 v[22:23], v[22:23], 0, s[26:27]
	global_load_dwordx4 v[48:51], v[22:23], off nt
	v_lshl_add_u64 v[22:23], v[22:23], 0, s[26:27]
	global_load_dwordx4 v[52:55], v[22:23], off nt
	global_load_dwordx4 v[56:59], v[142:143], off nt
	v_lshl_add_u64 v[142:143], v[142:143], 0, s[26:27]
	global_load_dwordx4 v[60:63], v[142:143], off nt
	v_lshl_add_u64 v[142:143], v[142:143], 0, s[26:27]
	global_load_dwordx4 v[64:67], v[142:143], off nt
	v_lshl_add_u64 v[142:143], v[142:143], 0, s[26:27]
	global_load_dwordx4 v[68:71], v[142:143], off nt
	v_lshl_add_u64 v[142:143], v[142:143], 0, s[26:27]
	global_load_dwordx4 v[72:75], v[142:143], off nt
	v_lshl_add_u64 v[142:143], v[142:143], 0, s[26:27]
	global_load_dwordx4 v[76:79], v[142:143], off nt
	v_lshl_add_u64 v[142:143], v[142:143], 0, s[26:27]
	global_load_dwordx4 v[80:83], v[142:143], off nt
	v_lshl_add_u64 v[142:143], v[142:143], 0, s[26:27]
	global_load_dwordx4 v[84:87], v[142:143], off nt
	s_branch .Lcvc_e1
.Lcvc_in1:
	s_sub_i32 s6, s4, 0xb00
	s_mul_i32 s7, s6, 0x38f
	s_lshr_b32 s7, s7, 16
	s_mul_i32 s8, s7, 0x48
	s_sub_i32 s6, s6, s8
	s_lshr_b32 s8, s6, 3
	s_lshl_b32 s8, s8, 8
	s_and_b32 s9, s6, 3
	s_lshl_b32 s9, s9, 6
	s_add_i32 s8, s8, s9
	s_bfe_u32 s9, s6, 0x10002
	s_lshl_b32 s9, s9, 5
	s_add_i32 s8, s8, s9
	s_lshl_b32 s8, s8, 2
	s_add_u32 s8, s8, 0x900000
	s_mul_i32 s9, s7, 0x90000
	s_add_u32 s10, s8, s9
	s_mov_b32 s11, 0
	v_lshl_add_u64 v[22:23], v[140:141], 0, s[10:11]
	s_mov_b64 s[26:27], 0x12000
	s_lshl_b32 s8, s6, 16
	s_lshl_b32 s9, s7, 7
	s_add_u32 s8, s8, s9
	s_add_u32 s8, s8, 0x4280000
	s_add_u32 s12, s22, s8
	s_addc_u32 s13, s23, 0
	s_mov_b32 s1, 0
	global_load_dwordx4 v[24:27], v[22:23], off nt
	v_lshl_add_u64 v[22:23], v[22:23], 0, s[26:27]
	global_load_dwordx4 v[28:31], v[22:23], off nt
	v_lshl_add_u64 v[22:23], v[22:23], 0, s[26:27]
	global_load_dwordx4 v[32:35], v[22:23], off nt
	v_lshl_add_u64 v[22:23], v[22:23], 0, s[26:27]
	global_load_dwordx4 v[36:39], v[22:23], off nt
	v_lshl_add_u64 v[22:23], v[22:23], 0, s[26:27]
	global_load_dwordx4 v[40:43], v[22:23], off nt
	v_lshl_add_u64 v[22:23], v[22:23], 0, s[26:27]
	global_load_dwordx4 v[44:47], v[22:23], off nt
	v_lshl_add_u64 v[22:23], v[22:23], 0, s[26:27]
	global_load_dwordx4 v[48:51], v[22:23], off nt
	v_lshl_add_u64 v[22:23], v[22:23], 0, s[26:27]
	global_load_dwordx4 v[52:55], v[22:23], off nt

.Lcvc_top:
	s_mov_b64 s[20:21], s[12:13]
	s_mov_b32 s0, s1
	s_cmp_eq_u32 s0, 0
	s_cbranch_scc1 .Lcvc_ws
	ds_write2_b32 v144, v24, v25 offset1:1
	ds_write2_b32 v144, v26, v27 offset0:2 offset1:3
	ds_write2_b32 v145, v28, v29 offset1:1
	ds_write2_b32 v145, v30, v31 offset0:2 offset1:3
	ds_write2_b32 v146, v32, v33 offset1:1
	ds_write2_b32 v146, v34, v35 offset0:2 offset1:3
	ds_write2_b32 v147, v36, v37 offset1:1
	ds_write2_b32 v147, v38, v39 offset0:2 offset1:3
	ds_write2_b32 v148, v40, v41 offset1:1
	ds_write2_b32 v148, v42, v43 offset0:2 offset1:3
	ds_write2_b32 v149, v44, v45 offset1:1
	ds_write2_b32 v149, v46, v47 offset0:2 offset1:3
	ds_write2_b32 v150, v48, v49 offset1:1
	ds_write2_b32 v150, v50, v51 offset0:2 offset1:3
	ds_write2_b32 v151, v52, v53 offset1:1
	ds_write2_b32 v151, v54, v55 offset0:2 offset1:3
	ds_write2_b32 v152, v56, v57 offset1:1
	ds_write2_b32 v152, v58, v59 offset0:2 offset1:3
	ds_write2_b32 v153, v60, v61 offset1:1
	ds_write2_b32 v153, v62, v63 offset0:2 offset1:3
	ds_write2_b32 v154, v64, v65 offset1:1
	ds_write2_b32 v154, v66, v67 offset0:2 offset1:3
	ds_write2_b32 v155, v68, v69 offset1:1
	ds_write2_b32 v155, v70, v71 offset0:2 offset1:3
	ds_write2_b32 v156, v72, v73 offset1:1
	ds_write2_b32 v156, v74, v75 offset0:2 offset1:3
	ds_write2_b32 v157, v76, v77 offset1:1
	ds_write2_b32 v157, v78, v79 offset0:2 offset1:3
	ds_write2_b32 v158, v80, v81 offset1:1
	ds_write2_b32 v158, v82, v83 offset0:2 offset1:3
	ds_write2_b32 v159, v84, v85 offset1:1
	ds_write2_b32 v159, v86, v87 offset0:2 offset1:3
	s_branch .Lcvc_wd
.Lcvc_ws:
	ds_write2_b32 v13, v24, v25 offset1:1
	ds_write2_b32 v13, v26, v27 offset0:2 offset1:3
	ds_write2_b32 v14, v28, v29 offset1:1
	ds_write2_b32 v14, v30, v31 offset0:2 offset1:3
	ds_write2_b32 v15, v32, v33 offset1:1
	ds_write2_b32 v15, v34, v35 offset0:2 offset1:3
	ds_write2_b32 v16, v36, v37 offset1:1
	ds_write2_b32 v16, v38, v39 offset0:2 offset1:3
	ds_write2_b32 v17, v40, v41 offset1:1
	ds_write2_b32 v17, v42, v43 offset0:2 offset1:3
	ds_write2_b32 v18, v44, v45 offset1:1
	ds_write2_b32 v18, v46, v47 offset0:2 offset1:3
	ds_write2_b32 v19, v48, v49 offset1:1
	ds_write2_b32 v19, v50, v51 offset0:2 offset1:3
	ds_write2_b32 v20, v52, v53 offset1:1
	ds_write2_b32 v20, v54, v55 offset0:2 offset1:3
.Lcvc_wd:
	s_add_i32 s4, s4, s24
	s_cmp_lt_u32 s4, s25
	s_cbranch_scc0 .Lcvc_noload
	s_cmpk_lt_u32 s4, 0xb00
	s_cbranch_scc0 .Lcvc_in2
	s_cmpk_gt_u32 s4, 0x57f
	s_cselect_b32 s5, 1, 0
	s_mul_i32 s6, s5, 0x580
	s_sub_i32 s6, s4, s6
	s_mul_i32 s7, s6, 0x2e9
	s_lshr_b32 s7, s7, 16
	s_mul_i32 s8, s7, 0x58
	s_sub_i32 s6, s6, s8
	s_lshr_b32 s8, s6, 2
	s_and_b32 s9, s6, 3
	s_lshl_b32 s10, s8, 9
	s_lshl_b32 s11, s9, 7
	s_add_i32 s10, s10, s11
	s_mul_i32 s11, s5, 0xb00000
	s_add_u32 s10, s10, s11
	s_add_u32 s10, s10, 0x1600000
	s_mul_i32 s11, s7, 0xb0000
	s_add_u32 s10, s10, s11
	s_mov_b32 s11, 0
	v_lshl_add_u64 v[22:23], v[136:137], 0, s[10:11]
	v_lshl_add_u64 v[142:143], v[138:139], 0, s[10:11]
	s_mov_b64 s[26:27], 0x16000
	s_lshl_b32 s8, s8, 3
	s_add_i32 s8, s8, s9
	s_mul_i32 s9, s5, 0xf80000
	s_lshl_b32 s8, s8, 16
	s_add_u32 s8, s8, s9
	s_lshl_b32 s9, s7, 7
	s_add_u32 s8, s8, s9
	s_add_u32 s8, s8, 0x3780000
	s_add_u32 s12, s22, s8
	s_addc_u32 s13, s23, 0
	s_mov_b32 s1, 1
	global_load_dwordx4 v[24:27], v[22:23], off nt
	v_lshl_add_u64 v[22:23], v[22:23], 0, s[26:27]
	global_load_dwordx4 v[28:31], v[22:23], off nt
	v_lshl_add_u64 v[22:23], v[22:23], 0, s[26:27]
	global_load_dwordx4 v[32:35], v[22:23], off nt
	v_lshl_add_u64 v[22:23], v[22:23], 0, s[26:27]
	global_load_dwordx4 v[36:39], v[22:23], off nt
	v_lshl_add_u64 v[22:23], v[22:23], 0, s[26:27]
	global_load_dwordx4 v[40:43], v[22:23], off nt
	v_lshl_add_u64 v[22:23], v[22:23], 0, s[26:27]
	global_load_dwordx4 v[44:47], v[22:23], off nt
	v_lshl_add_u64 v[22:23], v[22:23], 0, s[26:27]
	global_load_dwordx4 v[48:51], v[22:23], off nt
	v_lshl_add_u64 v[22:23], v[22:23], 0, s[26:27]
	global_load_dwordx4 v[52:55], v[22:23], off nt
	global_load_dwordx4 v[56:59], v[142:143], off nt
	v_lshl_add_u64 v[142:143], v[142:143], 0, s[26:27]
	global_load_dwordx4 v[60:63], v[142:143], off nt
	v_lshl_add_u64 v[142:143], v[142:143], 0, s[26:27]
	global_load_dwordx4 v[64:67], v[142:143], off nt
	v_lshl_add_u64 v[142:143], v[142:143], 0, s[26:27]
	global_load_dwordx4 v[68:71], v[142:143], off nt
	v_lshl_add_u64 v[142:143], v[142:143], 0, s[26:27]
	global_load_dwordx4 v[72:75], v[142:143], off nt
	v_lshl_add_u64 v[142:143], v[142:143], 0, s[26:27]
	global_load_dwordx4 v[76:79], v[142:143], off nt
	v_lshl_add_u64 v[142:143], v[142:143], 0, s[26:27]
	global_load_dwordx4 v[80:83], v[142:143], off nt
	v_lshl_add_u64 v[142:143], v[142:143], 0, s[26:27]
	global_load_dwordx4 v[84:87], v[142:143], off nt
	s_branch .Lcvc_e2

.LBB0_817:
	v_readlane_b32 s0, v253, 45
	v_readlane_b32 s1, v253, 46
	s_mulk_i32 s0, 0x4200
	s_add_i32 s4, s97, s0
	v_readlane_b32 s0, v253, 41
	v_readlane_b32 s1, v253, 42
	s_add_u32 s5, s0, 0x1000000
	s_addc_u32 s6, s1, 0
	v_and_b32_e32 v0, 3, v237
	v_and_b32_e32 v19, 16, v237
	v_lshrrev_b32_e32 v3, 5, v238
	v_lshrrev_b32_e32 v14, 3, v238
	v_lshlrev_b32_e32 v4, 3, v238
	s_cmpk_gt_i32 s10, 0x1a7f
	v_lshrrev_b32_e32 v22, 2, v237
	v_and_b32_e32 v8, 31, v237
	v_and_or_b32 v15, v2, 24, v0
	v_cmp_eq_u32_e32 vcc, 0, v19
	v_mul_u32_u24_e32 v21, 0x84, v3
	v_and_b32_e32 v2, 56, v4
	v_lshlrev_b32_e32 v20, 2, v14
	v_or_b32_e32 v16, 8, v14
	v_or_b32_e32 v17, 16, v14
	v_or_b32_e32 v18, 24, v14
	s_cbranch_scc1 .LBB0_824
	v_readlane_b32 s0, v253, 43
	v_readlane_b32 s1, v253, 45
	s_lshl_b32 s4, s0, 3
	s_add_i32 s4, s4, s1
	s_sub_i32 s4, 0x7ff, s4
	s_movk_i32 s24, 0x800
	s_movk_i32 s25, 0xf80
	v_readlane_b32 s0, v253, 45
	s_mulk_i32 s0, 0x4200
	s_add_i32 s0, s97, s0
	v_readlane_b32 s22, v253, 41
	v_readlane_b32 s23, v253, 42
	v_readlane_b32 s6, v252, 1
	v_readlane_b32 s7, v252, 2
	s_load_dwordx4 s[8:11], s[6:7], 0x48
	s_load_dwordx2 s[14:15], s[6:7], 0x60
	v_lshrrev_b32_e32 v12, 3, v238
	v_and_b32_e32 v7, 7, v238
	v_lshlrev_b32_e32 v11, 3, v7
	v_lshlrev_b32_e32 v10, 1, v11
	v_lshl_add_u32 v4, v12, 11, v10
	v_mul_u32_u24_e32 v2, 0x84, v12
	v_lshrrev_b32_e32 v8, 1, v7
	v_and_b32_e32 v9, 1, v7
	v_lshlrev_b32_e32 v0, 4, v8
	v_lshl_add_u32 v0, v9, 6, v0
	v_add3_u32 v13, s0, v0, v2
	v_add_u32_e32 v14, 0x420, v13
	v_add_u32_e32 v15, 0x840, v13
	v_add_u32_e32 v16, 0xc60, v13
	v_add_u32_e32 v17, 0x1080, v13
	v_add_u32_e32 v18, 0x14a0, v13
	v_add_u32_e32 v19, 0x18c0, v13
	v_add_u32_e32 v20, 0x1ce0, v13
	v_mul_u32_u24_e32 v3, 0x2100, v9
	v_lshl_add_u32 v0, v8, 4, v3
	v_add3_u32 v144, s0, v0, v2
	v_add_u32_e32 v145, 0x420, v144
	v_add_u32_e32 v146, 0x840, v144
	v_add_u32_e32 v147, 0xc60, v144
	v_add_u32_e32 v148, 0x1080, v144
	v_add_u32_e32 v149, 0x14a0, v144
	v_add_u32_e32 v150, 0x18c0, v144
	v_add_u32_e32 v151, 0x1ce0, v144
	v_add_u32_e32 v152, 64, v144
	v_add_u32_e32 v153, 64, v145
	v_add_u32_e32 v154, 64, v146
	v_add_u32_e32 v155, 64, v147
	v_add_u32_e32 v156, 64, v148
	v_add_u32_e32 v157, 64, v149
	v_add_u32_e32 v158, 64, v150
	v_add_u32_e32 v159, 64, v151
	v_mul_u32_u24_e32 v10, 0x84, v11
	v_lshlrev_b32_e32 v2, 2, v12
	v_add3_u32 v21, s0, v10, v2
	v_mov_b32_e32 v11, v1
	v_lshlrev_b32_e32 v8, 4, v7
	s_waitcnt lgkmcnt(0)
	v_mul_u32_u24_e32 v10, 0x2c00, v12
	v_add_u32_e32 v10, v10, v8
	v_lshl_add_u64 v[136:137], s[8:9], 0, v[10:11]
	v_lshl_add_u64 v[138:139], s[10:11], 0, v[10:11]
	v_mul_u32_u24_e32 v10, 0x2400, v12
	v_add_u32_e32 v10, v10, v8
	v_lshl_add_u64 v[140:141], s[14:15], 0, v[10:11]
	s_cmpk_lt_u32 s4, 0xb00
	s_cbranch_scc0 .Lcvp_in1
	s_cmpk_gt_u32 s4, 0x57f
	s_cselect_b32 s5, 1, 0
	s_mul_i32 s6, s5, 0x580
	s_sub_i32 s6, s4, s6
	s_mul_i32 s7, s6, 0x2e9
	s_lshr_b32 s7, s7, 16
	s_mul_i32 s8, s7, 0x58
	s_sub_i32 s6, s6, s8
	s_lshr_b32 s8, s6, 2
	s_and_b32 s9, s6, 3
	s_lshl_b32 s10, s8, 9
	s_lshl_b32 s11, s9, 7
	s_add_i32 s10, s10, s11
	s_mul_i32 s11, s5, 0xb00000
	s_add_u32 s10, s10, s11
	s_mul_i32 s11, s7, 0xb0000
	s_add_u32 s10, s10, s11
	s_mov_b32 s11, 0
	v_lshl_add_u64 v[22:23], v[136:137], 0, s[10:11]
	v_lshl_add_u64 v[142:143], v[138:139], 0, s[10:11]
	s_mov_b64 s[26:27], 0x16000
	s_lshl_b32 s8, s8, 3
	s_add_i32 s8, s8, s9
	s_mul_i32 s9, s5, 0xf80000
	s_lshl_b32 s8, s8, 16
	s_add_u32 s8, s8, s9
	s_lshl_b32 s9, s7, 7
	s_add_u32 s8, s8, s9
	s_add_u32 s8, s8, 0x1000000
	s_add_u32 s12, s22, s8
	s_addc_u32 s13, s23, 0
	s_mov_b32 s1, 1
	global_load_dwordx4 v[24:27], v[22:23], off nt
	v_lshl_add_u64 v[22:23], v[22:23], 0, s[26:27]
	global_load_dwordx4 v[28:31], v[22:23], off nt
	v_lshl_add_u64 v[22:23], v[22:23], 0, s[26:27]
	global_load_dwordx4 v[32:35], v[22:23], off nt
	v_lshl_add_u64 v[22:23], v[22:23], 0, s[26:27]
	global_load_dwordx4 v[36:39], v[22:23], off nt
	v_lshl_add_u64 v[22:23], v[22:23], 0, s[26:27]
	global_load_dwordx4 v[40:43], v[22:23], off nt
	v_lshl_add_u64 v[22:23], v[22:23], 0, s[26:27]
	global_load_dwordx4 v[44:47], v[22:23], off nt
	v_lshl_add_u64 v[22:23], v[22:23], 0, s[26:27]
	global_load_dwordx4 v[48:51], v[22:23], off nt
	v_lshl_add_u64 v[22:23], v[22:23], 0, s[26:27]
	global_load_dwordx4 v[52:55], v[22:23], off nt
	global_load_dwordx4 v[56:59], v[142:143], off nt
	v_lshl_add_u64 v[142:143], v[142:143], 0, s[26:27]
	global_load_dwordx4 v[60:63], v[142:143], off nt
	v_lshl_add_u64 v[142:143], v[142:143], 0, s[26:27]
	global_load_dwordx4 v[64:67], v[142:143], off nt
	v_lshl_add_u64 v[142:143], v[142:143], 0, s[26:27]
	global_load_dwordx4 v[68:71], v[142:143], off nt
	v_lshl_add_u64 v[142:143], v[142:143], 0, s[26:27]
	global_load_dwordx4 v[72:75], v[142:143], off nt
	v_lshl_add_u64 v[142:143], v[142:143], 0, s[26:27]
	global_load_dwordx4 v[76:79], v[142:143], off nt
	v_lshl_add_u64 v[142:143], v[142:143], 0, s[26:27]
	global_load_dwordx4 v[80:83], v[142:143], off nt
	v_lshl_add_u64 v[142:143], v[142:143], 0, s[26:27]
	global_load_dwordx4 v[84:87], v[142:143], off nt
	s_branch .Lcvp_e1
.Lcvp_in1:
	s_sub_i32 s6, s4, 0xb00
	s_mul_i32 s7, s6, 0x38f
	s_lshr_b32 s7, s7, 16
	s_mul_i32 s8, s7, 0x48
	s_sub_i32 s6, s6, s8
	s_lshr_b32 s8, s6, 3
	s_lshl_b32 s8, s8, 8
	s_and_b32 s9, s6, 3
	s_lshl_b32 s9, s9, 6
	s_add_i32 s8, s8, s9
	s_bfe_u32 s9, s6, 0x10002
	s_lshl_b32 s9, s9, 5
	s_add_i32 s8, s8, s9
	s_lshl_b32 s8, s8, 2
	s_mul_i32 s9, s7, 0x90000
	s_add_u32 s10, s8, s9
	s_mov_b32 s11, 0
	v_lshl_add_u64 v[22:23], v[140:141], 0, s[10:11]
	s_mov_b64 s[26:27], 0x12000
	s_lshl_b32 s8, s6, 16
	s_lshl_b32 s9, s7, 7
	s_add_u32 s8, s8, s9
	s_add_u32 s8, s8, 0x1b00000
	s_add_u32 s12, s22, s8
	s_addc_u32 s13, s23, 0
	s_mov_b32 s1, 0
	global_load_dwordx4 v[24:27], v[22:23], off nt
	v_lshl_add_u64 v[22:23], v[22:23], 0, s[26:27]
	global_load_dwordx4 v[28:31], v[22:23], off nt
	v_lshl_add_u64 v[22:23], v[22:23], 0, s[26:27]
	global_load_dwordx4 v[32:35], v[22:23], off nt
	v_lshl_add_u64 v[22:23], v[22:23], 0, s[26:27]
	global_load_dwordx4 v[36:39], v[22:23], off nt
	v_lshl_add_u64 v[22:23], v[22:23], 0, s[26:27]
	global_load_dwordx4 v[40:43], v[22:23], off nt
	v_lshl_add_u64 v[22:23], v[22:23], 0, s[26:27]
	global_load_dwordx4 v[44:47], v[22:23], off nt
	v_lshl_add_u64 v[22:23], v[22:23], 0, s[26:27]
	global_load_dwordx4 v[48:51], v[22:23], off nt
	v_lshl_add_u64 v[22:23], v[22:23], 0, s[26:27]
	global_load_dwordx4 v[52:55], v[22:23], off nt

.Lcvp_wd:
	s_add_i32 s4, s4, s24
	s_cmp_lt_u32 s4, s25
	s_cbranch_scc0 .Lcvp_noload
	s_cmpk_lt_u32 s4, 0xb00
	s_cbranch_scc0 .Lcvp_in2
	s_cmpk_gt_u32 s4, 0x57f
	s_cselect_b32 s5, 1, 0
	s_mul_i32 s6, s5, 0x580
	s_sub_i32 s6, s4, s6
	s_mul_i32 s7, s6, 0x2e9
	s_lshr_b32 s7, s7, 16
	s_mul_i32 s8, s7, 0x58
	s_sub_i32 s6, s6, s8
	s_lshr_b32 s8, s6, 2
	s_and_b32 s9, s6, 3
	s_lshl_b32 s10, s8, 9
	s_lshl_b32 s11, s9, 7
	s_add_i32 s10, s10, s11
	s_mul_i32 s11, s5, 0xb00000
	s_add_u32 s10, s10, s11
	s_mul_i32 s11, s7, 0xb0000
	s_add_u32 s10, s10, s11
	s_mov_b32 s11, 0
	v_lshl_add_u64 v[22:23], v[136:137], 0, s[10:11]
	v_lshl_add_u64 v[142:143], v[138:139], 0, s[10:11]
	s_mov_b64 s[26:27], 0x16000
	s_lshl_b32 s8, s8, 3
	s_add_i32 s8, s8, s9
	s_mul_i32 s9, s5, 0xf80000
	s_lshl_b32 s8, s8, 16
	s_add_u32 s8, s8, s9
	s_lshl_b32 s9, s7, 7
	s_add_u32 s8, s8, s9
	s_add_u32 s8, s8, 0x1000000
	s_add_u32 s12, s22, s8
	s_addc_u32 s13, s23, 0
	s_mov_b32 s1, 1
	global_load_dwordx4 v[24:27], v[22:23], off nt
	v_lshl_add_u64 v[22:23], v[22:23], 0, s[26:27]
	global_load_dwordx4 v[28:31], v[22:23], off nt
	v_lshl_add_u64 v[22:23], v[22:23], 0, s[26:27]
	global_load_dwordx4 v[32:35], v[22:23], off nt
	v_lshl_add_u64 v[22:23], v[22:23], 0, s[26:27]
	global_load_dwordx4 v[36:39], v[22:23], off nt
	v_lshl_add_u64 v[22:23], v[22:23], 0, s[26:27]
	global_load_dwordx4 v[40:43], v[22:23], off nt
	v_lshl_add_u64 v[22:23], v[22:23], 0, s[26:27]
	global_load_dwordx4 v[44:47], v[22:23], off nt
	v_lshl_add_u64 v[22:23], v[22:23], 0, s[26:27]
	global_load_dwordx4 v[48:51], v[22:23], off nt
	v_lshl_add_u64 v[22:23], v[22:23], 0, s[26:27]
	global_load_dwordx4 v[52:55], v[22:23], off nt
	global_load_dwordx4 v[56:59], v[142:143], off nt
	v_lshl_add_u64 v[142:143], v[142:143], 0, s[26:27]
	global_load_dwordx4 v[60:63], v[142:143], off nt
	v_lshl_add_u64 v[142:143], v[142:143], 0, s[26:27]
	global_load_dwordx4 v[64:67], v[142:143], off nt
	v_lshl_add_u64 v[142:143], v[142:143], 0, s[26:27]
	global_load_dwordx4 v[68:71], v[142:143], off nt
	v_lshl_add_u64 v[142:143], v[142:143], 0, s[26:27]
	global_load_dwordx4 v[72:75], v[142:143], off nt
	v_lshl_add_u64 v[142:143], v[142:143], 0, s[26:27]
	global_load_dwordx4 v[76:79], v[142:143], off nt
	v_lshl_add_u64 v[142:143], v[142:143], 0, s[26:27]
	global_load_dwordx4 v[80:83], v[142:143], off nt
	v_lshl_add_u64 v[142:143], v[142:143], 0, s[26:27]
	global_load_dwordx4 v[84:87], v[142:143], off nt
	s_branch .Lcvp_e2
